# v13 plus attention row-sum adds in the MFMA shadow plus GQA fragment reads fed through the QK MFMA gaps
# speedup vs baseline: 1.0117x; 1.0117x over previous
.LBB0_584:
	ds_read_b128 v[32:35], v194 offset:17408
	ds_read_b128 v[36:39], v194 offset:22016
	ds_read_b128 v[140:143], v194 offset:17440
	ds_read_b128 v[146:149], v194 offset:22048
	s_waitcnt lgkmcnt(3)
	v_mfma_f32_32x32x16_bf16 v[48:63], v[32:35], v[64:67], 0
	v_add_f32_e32 v222, v96, v97
	v_add_f32_e32 v223, v109, v110
	v_add_f32_e32 v222, v98, v222
	v_add_f32_e32 v223, v111, v223
	s_andn2_b64 vcc, exec, s[10:11]
	ds_read_b128 v[152:155], v194 offset:17472
	s_waitcnt lgkmcnt(3)
	v_mfma_f32_32x32x16_bf16 v[32:47], v[36:39], v[64:67], 0
	v_add_f32_e32 v222, v99, v222
	v_add_f32_e32 v223, v114, v223
	v_add_f32_e32 v222, v104, v222
	v_add_f32_e32 v223, v115, v223
	ds_read_b128 v[160:163], v194 offset:22080
	s_waitcnt lgkmcnt(3)
	v_mfma_f32_32x32x16_bf16 v[48:63], v[140:143], v[68:71], v[48:63]
	v_add_f32_e32 v222, v105, v222
	v_add_f32_e32 v223, v116, v223
	v_add_f32_e32 v222, v106, v222
	v_add_f32_e32 v223, v117, v223
	ds_read_b128 v[156:159], v194 offset:17504
	s_waitcnt lgkmcnt(3)
	v_mfma_f32_32x32x16_bf16 v[32:47], v[146:149], v[68:71], v[32:47]
	v_add_f32_e32 v222, v107, v222
	v_add_f32_e32 v223, v118, v223
	v_add_f32_e32 v222, v119, v222
	v_add_f32_e32 v223, v138, v223
	ds_read_b128 v[164:167], v194 offset:22112
	s_waitcnt lgkmcnt(3)
	v_mfma_f32_32x32x16_bf16 v[48:63], v[152:155], v[72:75], v[48:63]
	v_add_f32_e32 v222, v120, v222
	v_add_f32_e32 v223, v137, v223
	v_add_f32_e32 v222, v126, v222
	v_add_f32_e32 v223, v136, v223
	ds_read_b64_tr_b16 v[168:169], v218 offset:26624
	ds_read_b64_tr_b16 v[170:171], v218 offset:27648
	s_waitcnt lgkmcnt(4)
	v_mfma_f32_32x32x16_bf16 v[32:47], v[160:163], v[72:75], v[32:47]
	v_add_f32_e32 v222, v125, v222
	v_add_f32_e32 v223, v134, v223
	v_add_f32_e32 v222, v124, v222
	v_add_f32_e32 v223, v131, v223
	ds_read_b64_tr_b16 v[174:175], v218 offset:27904
	ds_read_b64_tr_b16 v[172:173], v218 offset:26880
	s_waitcnt lgkmcnt(5)
	v_mfma_f32_32x32x16_bf16 v[48:63], v[156:159], v[76:79], v[48:63]
	v_add_f32_e32 v222, v123, v222
	v_add_f32_e32 v223, v135, v223
	v_add_f32_e32 v222, v122, v222
	v_add_f32_e32 v223, v133, v223
	ds_read_b64_tr_b16 v[176:177], v218 offset:28672
	ds_read_b64_tr_b16 v[178:179], v218 offset:29696
	s_waitcnt lgkmcnt(6)
	v_mfma_f32_32x32x16_bf16 v[32:47], v[164:167], v[76:79], v[32:47]
	ds_read_b64_tr_b16 v[182:183], v218 offset:29952
	ds_read_b64_tr_b16 v[180:181], v218 offset:28928
	ds_read_b64_tr_b16 v[184:185], v218 offset:30720
	ds_read_b64_tr_b16 v[186:187], v218 offset:31744
	ds_read_b64_tr_b16 v[190:191], v218 offset:32000
	ds_read_b64_tr_b16 v[188:189], v218 offset:30976
	ds_read_b64_tr_b16 v[196:197], v218 offset:32768
	ds_read_b64_tr_b16 v[198:199], v218 offset:33792
	ds_read_b64_tr_b16 v[202:203], v218 offset:34048
	ds_read_b64_tr_b16 v[200:201], v218 offset:33024
	v_add_f32_e32 v222, v121, v222
	v_add_f32_e32 v223, v127, v223
	v_add_f32_e32 v222, v222, v223
	s_nop 10
	v_exp_f32_e32 v48, v48
	v_exp_f32_e32 v141, v58
	v_exp_f32_e32 v140, v59
	v_exp_f32_e32 v60, v60
	v_exp_f32_e32 v59, v61
	v_exp_f32_e32 v58, v62
	v_exp_f32_e32 v139, v32
	v_exp_f32_e32 v32, v49
	v_exp_f32_e32 v49, v33
	v_exp_f32_e32 v33, v50
	v_exp_f32_e32 v50, v34
	v_exp_f32_e32 v34, v51
	v_exp_f32_e32 v51, v35
	v_exp_f32_e32 v35, v52
	v_exp_f32_e32 v52, v36
	v_exp_f32_e32 v36, v53
	v_exp_f32_e32 v53, v37
	v_exp_f32_e32 v37, v54
	v_exp_f32_e32 v54, v38
	v_exp_f32_e32 v38, v55
	v_cvt_pk_bf16_f32 v146, v48, v32
	v_cvt_pk_bf16_f32 v147, v33, v34
	v_cvt_pk_bf16_f32 v148, v35, v36
	v_cvt_pk_bf16_f32 v149, v37, v38
	v_exp_f32_e32 v39, v39
	s_waitcnt lgkmcnt(14)
	v_mfma_f32_32x32x16_bf16 v[0:15], v[168:171], v[146:149], v[0:15]
	v_exp_f32_e32 v55, v56
	v_exp_f32_e32 v56, v57
	v_exp_f32_e32 v57, v63
	v_cvt_pk_bf16_f32 v152, v139, v49
	v_cvt_pk_bf16_f32 v153, v50, v51
	v_cvt_pk_bf16_f32 v154, v52, v53
	v_cvt_pk_bf16_f32 v155, v54, v39
	s_waitcnt lgkmcnt(12)
	v_mfma_f32_32x32x16_bf16 v[16:31], v[172:175], v[146:149], v[16:31]
	v_cvt_pk_bf16_f32 v146, v55, v56
	v_cvt_pk_bf16_f32 v147, v141, v140
	v_cvt_pk_bf16_f32 v148, v60, v59
	v_cvt_pk_bf16_f32 v149, v58, v57
	v_exp_f32_e32 v63, v40
	v_exp_f32_e32 v62, v41
	v_exp_f32_e32 v61, v42
	s_waitcnt lgkmcnt(10)
	v_mfma_f32_32x32x16_bf16 v[0:15], v[176:179], v[146:149], v[0:15]
	v_exp_f32_e32 v43, v43
	v_exp_f32_e32 v41, v44
	v_exp_f32_e32 v44, v45
	v_exp_f32_e32 v42, v46
	v_exp_f32_e32 v40, v47
	s_waitcnt lgkmcnt(8)
	v_mfma_f32_32x32x16_bf16 v[16:31], v[180:183], v[146:149], v[16:31]
	v_add_f32_e32 v224, v48, v32
	v_add_f32_e32 v225, v139, v49
	v_add_f32_e32 v224, v33, v224
	v_add_f32_e32 v225, v50, v225
	v_add_f32_e32 v224, v34, v224
	v_add_f32_e32 v225, v51, v225
	v_add_f32_e32 v224, v35, v224
	v_add_f32_e32 v225, v52, v225
	v_cvt_pk_bf16_f32 v146, v63, v62
	v_cvt_pk_bf16_f32 v147, v61, v43
	v_cvt_pk_bf16_f32 v148, v41, v44
	v_cvt_pk_bf16_f32 v149, v42, v40
	s_waitcnt lgkmcnt(6)
	v_mfma_f32_32x32x16_bf16 v[0:15], v[184:187], v[152:155], v[0:15]
	v_add_f32_e32 v224, v36, v224
	v_add_f32_e32 v225, v53, v225
	v_add_f32_e32 v224, v37, v224
	v_add_f32_e32 v225, v54, v225
	v_add_f32_e32 v224, v38, v224
	v_add_f32_e32 v225, v39, v225
	v_add_f32_e32 v224, v55, v224
	v_add_f32_e32 v225, v63, v225
	s_waitcnt lgkmcnt(4)
	v_mfma_f32_32x32x16_bf16 v[16:31], v[188:191], v[152:155], v[16:31]
	v_add_f32_e32 v224, v56, v224
	v_add_f32_e32 v225, v62, v225
	v_add_f32_e32 v224, v141, v224
	v_add_f32_e32 v225, v61, v225
	v_add_f32_e32 v224, v140, v224
	v_add_f32_e32 v225, v43, v225
	v_add_f32_e32 v224, v60, v224
	v_add_f32_e32 v225, v41, v225
	s_waitcnt lgkmcnt(2)
	v_mfma_f32_32x32x16_bf16 v[0:15], v[196:199], v[146:149], v[0:15]
	v_add_f32_e32 v224, v59, v224
	v_add_f32_e32 v225, v44, v225
	v_add_f32_e32 v224, v58, v224
	v_add_f32_e32 v225, v42, v225
	v_add_f32_e32 v224, v57, v224
	v_add_f32_e32 v225, v40, v225
	v_add_f32_e32 v224, v224, v225
	s_waitcnt lgkmcnt(0)
	v_mfma_f32_32x32x16_bf16 v[16:31], v[200:203], v[146:149], v[16:31]
	s_cbranch_vccnz .LBB0_586
	s_cmp_ge_u32 s14, s12
	s_cbranch_scc1 .Lgqa_w1_tail
	s_waitcnt vmcnt(3)
	ds_write_b128 v193, v[80:83]
	s_waitcnt vmcnt(2)
	ds_write_b128 v219, v[84:87] offset:9216
	s_branch .LBB0_586
